# V pass output stores: 32-bit offset (token<<13 | column bytes) with SGPR base instead of 64-bit VALU address chain, on top of U/V DPP-permlane reduces
# baseline (speedup 1.0000x reference)
.Lvx_skip:
	v_pk_fma_f32 v[86:87], v[128:129], v[86:87], v[94:95] op_sel_hi:[0,1,1]
	v_pk_fma_f32 v[90:91], v[128:129], v[90:91], v[98:99] op_sel_hi:[0,1,1]
	v_pk_fma_f32 v[94:95], v[128:129], v[96:97], v[100:101] op_sel_hi:[0,1,1]
	v_pk_fma_f32 v[76:77], v[128:129], v[76:77], v[80:81] op_sel_hi:[0,1,1]
	v_cvt_pk_f32_fp8_e32 v[80:81], v78
	v_cvt_pk_f32_fp8_sdwa v[96:97], v78 src0_sel:WORD_1
	v_cvt_pk_f32_fp8_e32 v[98:99], v79
	v_cvt_pk_f32_fp8_sdwa v[78:79], v79 src0_sel:WORD_1
	v_pk_fma_f32 v[80:81], v[128:129], v[80:81], v[84:85] op_sel_hi:[0,1,1]
	v_pk_fma_f32 v[84:85], v[128:129], v[96:97], v[88:89] op_sel_hi:[0,1,1]
	v_pk_fma_f32 v[88:89], v[128:129], v[98:99], v[92:93] op_sel_hi:[0,1,1]
	v_pk_fma_f32 v[78:79], v[128:129], v[78:79], v[82:83] op_sel_hi:[0,1,1]
	v_cvt_pk_f32_fp8_e32 v[82:83], v72
	v_cvt_pk_f32_fp8_sdwa v[92:93], v72 src0_sel:WORD_1
	v_cvt_pk_f32_fp8_e32 v[96:97], v73
	v_cvt_pk_f32_fp8_sdwa v[72:73], v73 src0_sel:WORD_1
	v_pk_fma_f32 v[82:83], v[128:129], v[82:83], v[86:87] op_sel:[1,0,0]
	v_pk_fma_f32 v[86:87], v[128:129], v[92:93], v[90:91] op_sel:[1,0,0]
	v_pk_fma_f32 v[90:91], v[128:129], v[96:97], v[94:95] op_sel:[1,0,0]
	v_pk_fma_f32 v[72:73], v[128:129], v[72:73], v[76:77] op_sel:[1,0,0]
	v_cvt_pk_f32_fp8_e32 v[76:77], v74
	v_cvt_pk_f32_fp8_sdwa v[92:93], v74 src0_sel:WORD_1
	v_cvt_pk_f32_fp8_e32 v[94:95], v75
	v_cvt_pk_f32_fp8_sdwa v[74:75], v75 src0_sel:WORD_1
	v_pk_fma_f32 v[76:77], v[128:129], v[76:77], v[80:81] op_sel:[1,0,0]
	v_pk_fma_f32 v[80:81], v[128:129], v[92:93], v[84:85] op_sel:[1,0,0]
	v_pk_fma_f32 v[84:85], v[128:129], v[94:95], v[88:89] op_sel:[1,0,0]
	v_pk_fma_f32 v[74:75], v[128:129], v[74:75], v[78:79] op_sel:[1,0,0]
	v_cvt_pk_f32_fp8_e32 v[78:79], v68
	v_cvt_pk_f32_fp8_sdwa v[88:89], v68 src0_sel:WORD_1
	v_cvt_pk_f32_fp8_e32 v[92:93], v69
	v_cvt_pk_f32_fp8_sdwa v[68:69], v69 src0_sel:WORD_1
	v_pk_fma_f32 v[78:79], v[130:131], v[78:79], v[82:83] op_sel_hi:[0,1,1]
	v_pk_fma_f32 v[82:83], v[130:131], v[88:89], v[86:87] op_sel_hi:[0,1,1]
	v_pk_fma_f32 v[86:87], v[130:131], v[92:93], v[90:91] op_sel_hi:[0,1,1]
	v_pk_fma_f32 v[68:69], v[130:131], v[68:69], v[72:73] op_sel_hi:[0,1,1]
	v_cvt_pk_f32_fp8_e32 v[72:73], v70
	v_cvt_pk_f32_fp8_sdwa v[88:89], v70 src0_sel:WORD_1
	v_cvt_pk_f32_fp8_e32 v[90:91], v71
	v_cvt_pk_f32_fp8_sdwa v[70:71], v71 src0_sel:WORD_1
	v_pk_fma_f32 v[72:73], v[130:131], v[72:73], v[76:77] op_sel_hi:[0,1,1]
	v_pk_fma_f32 v[76:77], v[130:131], v[88:89], v[80:81] op_sel_hi:[0,1,1]
	v_pk_fma_f32 v[80:81], v[130:131], v[90:91], v[84:85] op_sel_hi:[0,1,1]
	v_cvt_pk_f32_fp8_e32 v[84:85], v64
	v_cvt_pk_f32_fp8_sdwa v[88:89], v64 src0_sel:WORD_1
	v_cvt_pk_f32_fp8_e32 v[90:91], v65
	v_cvt_pk_f32_fp8_sdwa v[64:65], v65 src0_sel:WORD_1
	v_pk_fma_f32 v[70:71], v[130:131], v[70:71], v[74:75] op_sel_hi:[0,1,1]
	v_mov_b32_e32 v74, v131
	v_pk_fma_f32 v[78:79], v[74:75], v[84:85], v[78:79] op_sel_hi:[0,1,1]
	v_pk_fma_f32 v[64:65], v[74:75], v[64:65], v[68:69] op_sel_hi:[0,1,1]
	v_cvt_pk_f32_fp8_e32 v[68:69], v66
	v_pk_fma_f32 v[82:83], v[74:75], v[88:89], v[82:83] op_sel_hi:[0,1,1]
	v_pk_fma_f32 v[84:85], v[74:75], v[90:91], v[86:87] op_sel_hi:[0,1,1]
	v_cvt_pk_f32_fp8_sdwa v[86:87], v66 src0_sel:WORD_1
	v_cvt_pk_f32_fp8_e32 v[88:89], v67
	v_cvt_pk_f32_fp8_sdwa v[66:67], v67 src0_sel:WORD_1
	v_pk_fma_f32 v[68:69], v[74:75], v[68:69], v[72:73] op_sel_hi:[0,1,1]
	v_pk_fma_f32 v[72:73], v[74:75], v[86:87], v[76:77] op_sel_hi:[0,1,1]
	v_pk_fma_f32 v[76:77], v[74:75], v[88:89], v[80:81] op_sel_hi:[0,1,1]
	v_pk_fma_f32 v[66:67], v[74:75], v[66:67], v[70:71] op_sel_hi:[0,1,1]
	v_permlane32_swap_b32 v78, v68
	v_permlane32_swap_b32 v79, v69
	v_permlane32_swap_b32 v82, v72
	v_permlane32_swap_b32 v83, v73
	v_permlane32_swap_b32 v84, v76
	v_permlane32_swap_b32 v85, v77
	v_permlane32_swap_b32 v64, v66
	v_permlane32_swap_b32 v65, v67
	v_pk_add_f32 v[68:69], v[78:79], v[68:69]
	v_pk_add_f32 v[70:71], v[82:83], v[72:73]
	v_pk_add_f32 v[72:73], v[84:85], v[76:77]
	v_pk_add_f32 v[64:65], v[64:65], v[66:67]
	s_nop 1
	v_permlane16_swap_b32 v68, v72
	v_permlane16_swap_b32 v69, v73
	v_permlane16_swap_b32 v70, v64
	v_permlane16_swap_b32 v71, v65
	v_pk_add_f32 v[66:67], v[68:69], v[72:73]
	v_pk_add_f32 v[64:65], v[70:71], v[64:65]
	v_and_b32_e32 v89, 0xffff0000, v212
	s_nop 1
	v_add_f32_dpp v64, v64, v64 row_ror:8 row_mask:0xf bank_mask:0xc
	v_add_f32_dpp v64, v66, v66 row_ror:8 row_mask:0xf bank_mask:0x3
	v_add_f32_dpp v65, v65, v65 row_ror:8 row_mask:0xf bank_mask:0xc
	v_add_f32_dpp v65, v67, v67 row_ror:8 row_mask:0xf bank_mask:0x3
	v_and_b32_e32 v91, 0xffff0000, v213
	v_lshlrev_b32_e32 v88, 16, v212
	v_lshlrev_b32_e32 v90, 16, v213
	v_readlane_b32 s98, v248, s59
	v_readlane_b32 s99, v249, s59
	v_pk_fma_f32 v[66:67], v[88:89], s[74:75], v[90:91] op_sel_hi:[1,0,1]
	v_pk_add_f32 v[66:67], v[66:67], s[98:99] op_sel_hi:[1,0] neg_lo:[0,1] neg_hi:[0,1]
	v_pk_mul_f32 v[66:67], s[98:99], v[66:67] op_sel:[1,0]
	s_waitcnt lgkmcnt(0)
	ds_bpermute_b32 v64, v250, v64
	ds_bpermute_b32 v65, v250, v65
	v_pk_fma_f32 v[66:67], v[66:67], v[178:179], v[180:181]
	v_lshl_or_b32 v70, v186, 13, v138
	s_waitcnt lgkmcnt(0)
	v_pk_fma_f32 v[64:65], v[66:67], s[74:75], v[64:65] op_sel_hi:[1,0,1]
	s_add_i32 s16, s16, 16
	s_addk_i32 s17, 0x100
	s_add_i32 s34, s34, 0x40000
	s_and_b64 vcc, exec, s[0:1]
	s_mov_b32 s0, s61
	global_store_dwordx2 v70, v[64:65], s[78:79] nt
	s_cbranch_vccnz .LBB0_938
.LBB0_934:
	s_add_i32 s15, s17, 0xffffff80
	s_and_b32 s15, s15, 0x780
	v_lshl_add_u32 v76, s15, 2, v189
	ds_read_b128 v[64:67], v76
	s_add_i32 s14, s34, 0xfffc0000
	s_add_i32 s1, s0, 1
	s_and_b32 s14, s14, 0x1e00000
	s_add_u32 s14, s38, s14
	s_waitcnt lgkmcnt(0)
	s_addc_u32 s15, s39, 0
	ds_read_b128 v[68:71], v76 offset:16
	ds_read_b128 v[72:75], v76 offset:32
	ds_read_b128 v[128:131], v76 offset:48
	v_lshl_or_b32 v65, v65, 7, v137
	v_lshl_or_b32 v64, v64, 7, v174
	global_load_dwordx4 v[124:127], v64, s[14:15]
	global_load_dwordx4 v[120:123], v65, s[14:15]
	v_lshl_or_b32 v64, v67, 7, v137
	v_lshl_or_b32 v65, v66, 7, v174
	global_load_dwordx4 v[116:119], v65, s[14:15]
	global_load_dwordx4 v[112:115], v64, s[14:15]
	s_waitcnt lgkmcnt(2)
	v_lshl_or_b32 v64, v69, 7, v137
	v_lshl_or_b32 v65, v68, 7, v174
	global_load_dwordx4 v[108:111], v65, s[14:15]
	global_load_dwordx4 v[104:107], v64, s[14:15]
	v_lshl_or_b32 v64, v71, 7, v137
	v_lshl_or_b32 v65, v70, 7, v174
	global_load_dwordx4 v[100:103], v65, s[14:15]
	global_load_dwordx4 v[96:99], v64, s[14:15]
	s_waitcnt lgkmcnt(1)
	v_lshl_or_b32 v64, v73, 7, v137
	v_lshl_or_b32 v65, v72, 7, v174
	global_load_dwordx4 v[92:95], v65, s[14:15]
	global_load_dwordx4 v[88:91], v64, s[14:15]
	s_and_b32 s59, s1, 15
	v_lshl_or_b32 v64, v75, 7, v137
	v_lshl_or_b32 v65, v74, 7, v174
	s_add_i32 s1, s16, -16
	v_or_b32_e32 v186, s59, v176
	global_load_dwordx4 v[84:87], v65, s[14:15]
	global_load_dwordx4 v[80:83], v64, s[14:15]
	s_waitcnt lgkmcnt(0)
	s_and_b32 s1, s1, 0x780
	v_lshl_or_b32 v64, v129, 7, v137
	v_lshl_or_b32 v65, v128, 7, v174
	v_or_b32_e32 v214, s1, v192
	global_load_dwordx4 v[76:79], v65, s[14:15]
	global_load_dwordx4 v[72:75], v64, s[14:15]
	v_lshlrev_b32_e32 v64, 7, v131
	v_lshlrev_b32_e32 v65, 7, v130
	v_or_b32_e32 v64, v64, v137
	v_or_b32_e32 v65, v65, v174
	s_and_b32 s1, s0, 14
	s_waitcnt vmcnt(30)
	v_cvt_pk_f32_fp8_e32 v[224:225], v0
	v_cvt_pk_f32_fp8_sdwa v[226:227], v0 src0_sel:WORD_1
	v_cvt_pk_f32_fp8_e32 v[228:229], v1
	v_cvt_pk_f32_fp8_sdwa v[230:231], v1 src0_sel:WORD_1
	global_load_dwordx4 v[68:71], v65, s[14:15]
	s_nop 0
	global_load_dwordx4 v[64:67], v64, s[14:15]
	v_lshl_add_u32 v128, s1, 9, v193
	s_waitcnt vmcnt(31)
	v_cvt_pk_f32_fp8_e32 v[240:241], v4
	v_cvt_pk_f32_fp8_sdwa v[242:243], v4 src0_sel:WORD_1
	v_cvt_pk_f32_fp8_e32 v[244:245], v5
	v_cvt_pk_f32_fp8_sdwa v[246:247], v5 src0_sel:WORD_1
	ds_read_b128 v[216:219], v128
	ds_read_b128 v[220:223], v128 offset:16
	ds_read_b128 v[132:135], v128 offset:32
	ds_read_b128 v[128:131], v128 offset:48
	v_cvt_pk_f32_fp8_e32 v[232:233], v2
	s_waitcnt lgkmcnt(3)
	v_pk_fma_f32 v[224:225], v[216:217], v[224:225], 0 op_sel_hi:[0,1,0]
	v_pk_fma_f32 v[226:227], v[216:217], v[226:227], 0 op_sel_hi:[0,1,0]
	v_pk_fma_f32 v[228:229], v[216:217], v[228:229], 0 op_sel_hi:[0,1,0]
	v_pk_fma_f32 v[230:231], v[216:217], v[230:231], 0 op_sel_hi:[0,1,0]
	v_cvt_pk_f32_fp8_sdwa v[234:235], v2 src0_sel:WORD_1
	v_cvt_pk_f32_fp8_e32 v[236:237], v3
	v_cvt_pk_f32_fp8_sdwa v[238:239], v3 src0_sel:WORD_1
	v_pk_fma_f32 v[224:225], v[216:217], v[240:241], v[224:225] op_sel:[1,0,0]
	v_pk_fma_f32 v[226:227], v[216:217], v[242:243], v[226:227] op_sel:[1,0,0]
	v_pk_fma_f32 v[228:229], v[216:217], v[244:245], v[228:229] op_sel:[1,0,0]
	v_pk_fma_f32 v[230:231], v[216:217], v[246:247], v[230:231] op_sel:[1,0,0]
	v_cvt_pk_f32_fp8_e32 v[240:241], v6
	v_cvt_pk_f32_fp8_sdwa v[242:243], v6 src0_sel:WORD_1
	v_cvt_pk_f32_fp8_e32 v[244:245], v7
	v_cvt_pk_f32_fp8_sdwa v[246:247], v7 src0_sel:WORD_1
	v_pk_fma_f32 v[232:233], v[216:217], v[232:233], 0 op_sel_hi:[0,1,0]
	v_pk_fma_f32 v[234:235], v[216:217], v[234:235], 0 op_sel_hi:[0,1,0]
	v_pk_fma_f32 v[236:237], v[216:217], v[236:237], 0 op_sel_hi:[0,1,0]
	v_pk_fma_f32 v[238:239], v[216:217], v[238:239], 0 op_sel_hi:[0,1,0]
	v_pk_fma_f32 v[232:233], v[216:217], v[240:241], v[232:233] op_sel:[1,0,0]
	v_pk_fma_f32 v[234:235], v[216:217], v[242:243], v[234:235] op_sel:[1,0,0]
	v_pk_fma_f32 v[236:237], v[216:217], v[244:245], v[236:237] op_sel:[1,0,0]
	v_pk_fma_f32 v[216:217], v[216:217], v[246:247], v[238:239] op_sel:[1,0,0]
	s_waitcnt vmcnt(30)
	v_cvt_pk_f32_fp8_e32 v[238:239], v8
	v_cvt_pk_f32_fp8_sdwa v[240:241], v8 src0_sel:WORD_1
	v_cvt_pk_f32_fp8_e32 v[242:243], v9
	v_cvt_pk_f32_fp8_sdwa v[244:245], v9 src0_sel:WORD_1
	v_pk_fma_f32 v[224:225], v[218:219], v[238:239], v[224:225] op_sel_hi:[0,1,1]
	v_pk_fma_f32 v[226:227], v[218:219], v[240:241], v[226:227] op_sel_hi:[0,1,1]
	v_pk_fma_f32 v[228:229], v[218:219], v[242:243], v[228:229] op_sel_hi:[0,1,1]
	v_pk_fma_f32 v[230:231], v[218:219], v[244:245], v[230:231] op_sel_hi:[0,1,1]
	v_cvt_pk_f32_fp8_e32 v[238:239], v10
	v_cvt_pk_f32_fp8_sdwa v[240:241], v10 src0_sel:WORD_1
	v_cvt_pk_f32_fp8_e32 v[242:243], v11
	v_cvt_pk_f32_fp8_sdwa v[244:245], v11 src0_sel:WORD_1
	v_pk_fma_f32 v[232:233], v[218:219], v[238:239], v[232:233] op_sel_hi:[0,1,1]
	v_pk_fma_f32 v[234:235], v[218:219], v[240:241], v[234:235] op_sel_hi:[0,1,1]
	v_pk_fma_f32 v[236:237], v[218:219], v[242:243], v[236:237] op_sel_hi:[0,1,1]
	v_pk_fma_f32 v[216:217], v[218:219], v[244:245], v[216:217] op_sel_hi:[0,1,1]
	v_mov_b32_e32 v138, v219
	s_waitcnt vmcnt(29)
	v_cvt_pk_f32_fp8_e32 v[218:219], v12
	v_cvt_pk_f32_fp8_sdwa v[238:239], v12 src0_sel:WORD_1
	v_cvt_pk_f32_fp8_e32 v[240:241], v13
	v_cvt_pk_f32_fp8_sdwa v[242:243], v13 src0_sel:WORD_1
	v_pk_fma_f32 v[218:219], v[138:139], v[218:219], v[224:225] op_sel_hi:[0,1,1]
	v_pk_fma_f32 v[224:225], v[138:139], v[238:239], v[226:227] op_sel_hi:[0,1,1]
	v_pk_fma_f32 v[226:227], v[138:139], v[240:241], v[228:229] op_sel_hi:[0,1,1]
	v_pk_fma_f32 v[228:229], v[138:139], v[242:243], v[230:231] op_sel_hi:[0,1,1]
	v_cvt_pk_f32_fp8_e32 v[230:231], v14
	v_cvt_pk_f32_fp8_sdwa v[238:239], v14 src0_sel:WORD_1
	v_cvt_pk_f32_fp8_e32 v[240:241], v15
	v_cvt_pk_f32_fp8_sdwa v[242:243], v15 src0_sel:WORD_1
	v_pk_fma_f32 v[230:231], v[138:139], v[230:231], v[232:233] op_sel_hi:[0,1,1]
	v_pk_fma_f32 v[232:233], v[138:139], v[238:239], v[234:235] op_sel_hi:[0,1,1]
	v_pk_fma_f32 v[234:235], v[138:139], v[240:241], v[236:237] op_sel_hi:[0,1,1]
	v_pk_fma_f32 v[216:217], v[138:139], v[242:243], v[216:217] op_sel_hi:[0,1,1]
	s_waitcnt vmcnt(28)
	v_cvt_pk_f32_fp8_e32 v[236:237], v16
	v_cvt_pk_f32_fp8_sdwa v[238:239], v16 src0_sel:WORD_1
	v_cvt_pk_f32_fp8_e32 v[240:241], v17
	v_cvt_pk_f32_fp8_sdwa v[242:243], v17 src0_sel:WORD_1
	s_waitcnt lgkmcnt(2)
	v_pk_fma_f32 v[218:219], v[220:221], v[236:237], v[218:219] op_sel_hi:[0,1,1]
	v_pk_fma_f32 v[224:225], v[220:221], v[238:239], v[224:225] op_sel_hi:[0,1,1]
	v_pk_fma_f32 v[226:227], v[220:221], v[240:241], v[226:227] op_sel_hi:[0,1,1]
	v_pk_fma_f32 v[228:229], v[220:221], v[242:243], v[228:229] op_sel_hi:[0,1,1]
	v_cvt_pk_f32_fp8_e32 v[236:237], v18
	v_cvt_pk_f32_fp8_sdwa v[238:239], v18 src0_sel:WORD_1
	v_cvt_pk_f32_fp8_e32 v[240:241], v19
	v_cvt_pk_f32_fp8_sdwa v[242:243], v19 src0_sel:WORD_1
	v_pk_fma_f32 v[230:231], v[220:221], v[236:237], v[230:231] op_sel_hi:[0,1,1]
	v_pk_fma_f32 v[232:233], v[220:221], v[238:239], v[232:233] op_sel_hi:[0,1,1]
	v_pk_fma_f32 v[234:235], v[220:221], v[240:241], v[234:235] op_sel_hi:[0,1,1]
	v_pk_fma_f32 v[216:217], v[220:221], v[242:243], v[216:217] op_sel_hi:[0,1,1]
	s_waitcnt vmcnt(27)
	v_cvt_pk_f32_fp8_e32 v[236:237], v20
	v_cvt_pk_f32_fp8_sdwa v[238:239], v20 src0_sel:WORD_1
	v_cvt_pk_f32_fp8_e32 v[240:241], v21
	v_cvt_pk_f32_fp8_sdwa v[242:243], v21 src0_sel:WORD_1
	v_pk_fma_f32 v[218:219], v[220:221], v[236:237], v[218:219] op_sel:[1,0,0]
	v_pk_fma_f32 v[224:225], v[220:221], v[238:239], v[224:225] op_sel:[1,0,0]
	v_pk_fma_f32 v[226:227], v[220:221], v[240:241], v[226:227] op_sel:[1,0,0]
	v_pk_fma_f32 v[228:229], v[220:221], v[242:243], v[228:229] op_sel:[1,0,0]
	v_cvt_pk_f32_fp8_e32 v[236:237], v22
	v_cvt_pk_f32_fp8_sdwa v[238:239], v22 src0_sel:WORD_1
	v_cvt_pk_f32_fp8_e32 v[240:241], v23
	v_cvt_pk_f32_fp8_sdwa v[242:243], v23 src0_sel:WORD_1
	v_pk_fma_f32 v[230:231], v[220:221], v[236:237], v[230:231] op_sel:[1,0,0]
	v_pk_fma_f32 v[232:233], v[220:221], v[238:239], v[232:233] op_sel:[1,0,0]
	v_pk_fma_f32 v[234:235], v[220:221], v[240:241], v[234:235] op_sel:[1,0,0]
	v_pk_fma_f32 v[216:217], v[220:221], v[242:243], v[216:217] op_sel:[1,0,0]
	s_waitcnt vmcnt(26)
	v_cvt_pk_f32_fp8_e32 v[220:221], v24
	v_cvt_pk_f32_fp8_sdwa v[236:237], v24 src0_sel:WORD_1
	v_cvt_pk_f32_fp8_e32 v[238:239], v25
	v_cvt_pk_f32_fp8_sdwa v[240:241], v25 src0_sel:WORD_1
	v_pk_fma_f32 v[218:219], v[222:223], v[220:221], v[218:219] op_sel_hi:[0,1,1]
	v_pk_fma_f32 v[220:221], v[222:223], v[236:237], v[224:225] op_sel_hi:[0,1,1]
	v_pk_fma_f32 v[224:225], v[222:223], v[238:239], v[226:227] op_sel_hi:[0,1,1]
	v_pk_fma_f32 v[226:227], v[222:223], v[240:241], v[228:229] op_sel_hi:[0,1,1]
	v_cvt_pk_f32_fp8_e32 v[228:229], v26
	v_cvt_pk_f32_fp8_sdwa v[236:237], v26 src0_sel:WORD_1
	v_cvt_pk_f32_fp8_e32 v[238:239], v27
	v_cvt_pk_f32_fp8_sdwa v[240:241], v27 src0_sel:WORD_1
	v_pk_fma_f32 v[228:229], v[222:223], v[228:229], v[230:231] op_sel_hi:[0,1,1]
	v_pk_fma_f32 v[230:231], v[222:223], v[236:237], v[232:233] op_sel_hi:[0,1,1]
	v_pk_fma_f32 v[232:233], v[222:223], v[238:239], v[234:235] op_sel_hi:[0,1,1]
	v_pk_fma_f32 v[216:217], v[222:223], v[240:241], v[216:217] op_sel_hi:[0,1,1]
	v_mov_b32_e32 v138, v223
	s_waitcnt vmcnt(25)
	v_cvt_pk_f32_fp8_e32 v[222:223], v28
	v_cvt_pk_f32_fp8_sdwa v[234:235], v28 src0_sel:WORD_1
	v_cvt_pk_f32_fp8_e32 v[236:237], v29
	v_cvt_pk_f32_fp8_sdwa v[238:239], v29 src0_sel:WORD_1
	v_pk_fma_f32 v[218:219], v[138:139], v[222:223], v[218:219] op_sel_hi:[0,1,1]
	v_pk_fma_f32 v[220:221], v[138:139], v[234:235], v[220:221] op_sel_hi:[0,1,1]
	v_pk_fma_f32 v[222:223], v[138:139], v[236:237], v[224:225] op_sel_hi:[0,1,1]
	v_pk_fma_f32 v[224:225], v[138:139], v[238:239], v[226:227] op_sel_hi:[0,1,1]
	v_cvt_pk_f32_fp8_e32 v[226:227], v30
	v_cvt_pk_f32_fp8_sdwa v[234:235], v30 src0_sel:WORD_1
	v_cvt_pk_f32_fp8_e32 v[236:237], v31
	v_cvt_pk_f32_fp8_sdwa v[238:239], v31 src0_sel:WORD_1
	v_pk_fma_f32 v[226:227], v[138:139], v[226:227], v[228:229] op_sel_hi:[0,1,1]
	v_pk_fma_f32 v[228:229], v[138:139], v[234:235], v[230:231] op_sel_hi:[0,1,1]
	v_pk_fma_f32 v[230:231], v[138:139], v[236:237], v[232:233] op_sel_hi:[0,1,1]
	v_pk_fma_f32 v[216:217], v[138:139], v[238:239], v[216:217] op_sel_hi:[0,1,1]
	s_waitcnt vmcnt(24)
	v_cvt_pk_f32_fp8_e32 v[232:233], v32
	v_cvt_pk_f32_fp8_sdwa v[234:235], v32 src0_sel:WORD_1
	v_cvt_pk_f32_fp8_e32 v[236:237], v33
	v_cvt_pk_f32_fp8_sdwa v[238:239], v33 src0_sel:WORD_1
	s_waitcnt lgkmcnt(1)
	v_pk_fma_f32 v[218:219], v[132:133], v[232:233], v[218:219] op_sel_hi:[0,1,1]
	v_pk_fma_f32 v[220:221], v[132:133], v[234:235], v[220:221] op_sel_hi:[0,1,1]
	v_pk_fma_f32 v[222:223], v[132:133], v[236:237], v[222:223] op_sel_hi:[0,1,1]
	v_pk_fma_f32 v[224:225], v[132:133], v[238:239], v[224:225] op_sel_hi:[0,1,1]
	v_cvt_pk_f32_fp8_e32 v[232:233], v34
	v_cvt_pk_f32_fp8_sdwa v[234:235], v34 src0_sel:WORD_1
	v_cvt_pk_f32_fp8_e32 v[236:237], v35
	v_cvt_pk_f32_fp8_sdwa v[238:239], v35 src0_sel:WORD_1
	v_pk_fma_f32 v[226:227], v[132:133], v[232:233], v[226:227] op_sel_hi:[0,1,1]
	v_pk_fma_f32 v[228:229], v[132:133], v[234:235], v[228:229] op_sel_hi:[0,1,1]
	v_pk_fma_f32 v[230:231], v[132:133], v[236:237], v[230:231] op_sel_hi:[0,1,1]
	v_pk_fma_f32 v[216:217], v[132:133], v[238:239], v[216:217] op_sel_hi:[0,1,1]
	s_waitcnt vmcnt(23)
	v_cvt_pk_f32_fp8_e32 v[232:233], v36
	v_cvt_pk_f32_fp8_sdwa v[234:235], v36 src0_sel:WORD_1
	v_cvt_pk_f32_fp8_e32 v[236:237], v37
	v_cvt_pk_f32_fp8_sdwa v[238:239], v37 src0_sel:WORD_1
	v_pk_fma_f32 v[218:219], v[132:133], v[232:233], v[218:219] op_sel:[1,0,0]
	v_pk_fma_f32 v[220:221], v[132:133], v[234:235], v[220:221] op_sel:[1,0,0]
	v_pk_fma_f32 v[222:223], v[132:133], v[236:237], v[222:223] op_sel:[1,0,0]
	v_pk_fma_f32 v[224:225], v[132:133], v[238:239], v[224:225] op_sel:[1,0,0]
	v_cvt_pk_f32_fp8_e32 v[232:233], v38
	v_cvt_pk_f32_fp8_sdwa v[234:235], v38 src0_sel:WORD_1
	v_cvt_pk_f32_fp8_e32 v[236:237], v39
	v_cvt_pk_f32_fp8_sdwa v[238:239], v39 src0_sel:WORD_1
	v_pk_fma_f32 v[226:227], v[132:133], v[232:233], v[226:227] op_sel:[1,0,0]
	v_pk_fma_f32 v[228:229], v[132:133], v[234:235], v[228:229] op_sel:[1,0,0]
	v_pk_fma_f32 v[230:231], v[132:133], v[236:237], v[230:231] op_sel:[1,0,0]
	v_pk_fma_f32 v[132:133], v[132:133], v[238:239], v[216:217] op_sel:[1,0,0]
	s_waitcnt vmcnt(22)
	v_cvt_pk_f32_fp8_e32 v[216:217], v40
	v_cvt_pk_f32_fp8_sdwa v[232:233], v40 src0_sel:WORD_1
	v_cvt_pk_f32_fp8_e32 v[234:235], v41
	v_cvt_pk_f32_fp8_sdwa v[236:237], v41 src0_sel:WORD_1
	v_pk_fma_f32 v[216:217], v[134:135], v[216:217], v[218:219] op_sel_hi:[0,1,1]
	v_pk_fma_f32 v[218:219], v[134:135], v[232:233], v[220:221] op_sel_hi:[0,1,1]
	v_pk_fma_f32 v[220:221], v[134:135], v[234:235], v[222:223] op_sel_hi:[0,1,1]
	v_pk_fma_f32 v[222:223], v[134:135], v[236:237], v[224:225] op_sel_hi:[0,1,1]
	v_cvt_pk_f32_fp8_e32 v[224:225], v42
	v_cvt_pk_f32_fp8_sdwa v[232:233], v42 src0_sel:WORD_1
	v_cvt_pk_f32_fp8_e32 v[234:235], v43
	v_cvt_pk_f32_fp8_sdwa v[236:237], v43 src0_sel:WORD_1
	v_pk_fma_f32 v[224:225], v[134:135], v[224:225], v[226:227] op_sel_hi:[0,1,1]
	v_pk_fma_f32 v[226:227], v[134:135], v[232:233], v[228:229] op_sel_hi:[0,1,1]
	v_pk_fma_f32 v[228:229], v[134:135], v[234:235], v[230:231] op_sel_hi:[0,1,1]
	v_pk_fma_f32 v[132:133], v[134:135], v[236:237], v[132:133] op_sel_hi:[0,1,1]
	s_waitcnt vmcnt(21)
	v_cvt_pk_f32_fp8_e32 v[230:231], v44
	v_cvt_pk_f32_fp8_sdwa v[232:233], v44 src0_sel:WORD_1
	v_cvt_pk_f32_fp8_e32 v[234:235], v45
	v_cvt_pk_f32_fp8_sdwa v[236:237], v45 src0_sel:WORD_1
	v_mov_b32_e32 v134, v135
	v_pk_fma_f32 v[216:217], v[134:135], v[230:231], v[216:217] op_sel_hi:[0,1,1]
	v_pk_fma_f32 v[218:219], v[134:135], v[232:233], v[218:219] op_sel_hi:[0,1,1]
	v_pk_fma_f32 v[220:221], v[134:135], v[234:235], v[220:221] op_sel_hi:[0,1,1]
	v_pk_fma_f32 v[222:223], v[134:135], v[236:237], v[222:223] op_sel_hi:[0,1,1]
	v_cvt_pk_f32_fp8_e32 v[230:231], v46
	v_cvt_pk_f32_fp8_sdwa v[232:233], v46 src0_sel:WORD_1
	v_cvt_pk_f32_fp8_e32 v[234:235], v47
	v_cvt_pk_f32_fp8_sdwa v[236:237], v47 src0_sel:WORD_1
	v_pk_fma_f32 v[224:225], v[134:135], v[230:231], v[224:225] op_sel_hi:[0,1,1]
	v_pk_fma_f32 v[226:227], v[134:135], v[232:233], v[226:227] op_sel_hi:[0,1,1]
	v_pk_fma_f32 v[228:229], v[134:135], v[234:235], v[228:229] op_sel_hi:[0,1,1]
	v_pk_fma_f32 v[132:133], v[134:135], v[236:237], v[132:133] op_sel_hi:[0,1,1]
	s_waitcnt vmcnt(20)
	v_cvt_pk_f32_fp8_e32 v[134:135], v48
	v_cvt_pk_f32_fp8_sdwa v[230:231], v48 src0_sel:WORD_1
	v_cvt_pk_f32_fp8_e32 v[232:233], v49
	v_cvt_pk_f32_fp8_sdwa v[234:235], v49 src0_sel:WORD_1
	s_waitcnt lgkmcnt(0)
	v_pk_fma_f32 v[134:135], v[128:129], v[134:135], v[216:217] op_sel_hi:[0,1,1]
	v_pk_fma_f32 v[216:217], v[128:129], v[230:231], v[218:219] op_sel_hi:[0,1,1]
	v_pk_fma_f32 v[218:219], v[128:129], v[232:233], v[220:221] op_sel_hi:[0,1,1]
	v_pk_fma_f32 v[220:221], v[128:129], v[234:235], v[222:223] op_sel_hi:[0,1,1]
	v_cvt_pk_f32_fp8_e32 v[222:223], v50
	v_cvt_pk_f32_fp8_sdwa v[230:231], v50 src0_sel:WORD_1
	v_cvt_pk_f32_fp8_e32 v[232:233], v51
	v_cvt_pk_f32_fp8_sdwa v[234:235], v51 src0_sel:WORD_1
	v_pk_fma_f32 v[222:223], v[128:129], v[222:223], v[224:225] op_sel_hi:[0,1,1]
	v_pk_fma_f32 v[224:225], v[128:129], v[230:231], v[226:227] op_sel_hi:[0,1,1]
	v_pk_fma_f32 v[226:227], v[128:129], v[232:233], v[228:229] op_sel_hi:[0,1,1]
	v_pk_fma_f32 v[132:133], v[128:129], v[234:235], v[132:133] op_sel_hi:[0,1,1]
	s_waitcnt vmcnt(19)
	v_cvt_pk_f32_fp8_e32 v[228:229], v52
	v_cvt_pk_f32_fp8_sdwa v[230:231], v52 src0_sel:WORD_1
	v_cvt_pk_f32_fp8_e32 v[232:233], v53
	v_cvt_pk_f32_fp8_sdwa v[234:235], v53 src0_sel:WORD_1
	v_pk_fma_f32 v[134:135], v[128:129], v[228:229], v[134:135] op_sel:[1,0,0]
	v_pk_fma_f32 v[216:217], v[128:129], v[230:231], v[216:217] op_sel:[1,0,0]
	v_pk_fma_f32 v[218:219], v[128:129], v[232:233], v[218:219] op_sel:[1,0,0]
	v_pk_fma_f32 v[220:221], v[128:129], v[234:235], v[220:221] op_sel:[1,0,0]
	v_cvt_pk_f32_fp8_e32 v[228:229], v54
	v_cvt_pk_f32_fp8_sdwa v[230:231], v54 src0_sel:WORD_1
	v_cvt_pk_f32_fp8_e32 v[232:233], v55
	v_cvt_pk_f32_fp8_sdwa v[234:235], v55 src0_sel:WORD_1
	v_pk_fma_f32 v[222:223], v[128:129], v[228:229], v[222:223] op_sel:[1,0,0]
	v_pk_fma_f32 v[224:225], v[128:129], v[230:231], v[224:225] op_sel:[1,0,0]
	v_pk_fma_f32 v[226:227], v[128:129], v[232:233], v[226:227] op_sel:[1,0,0]
	v_pk_fma_f32 v[128:129], v[128:129], v[234:235], v[132:133] op_sel:[1,0,0]
	s_waitcnt vmcnt(18)
	v_cvt_pk_f32_fp8_e32 v[132:133], v56
	v_cvt_pk_f32_fp8_sdwa v[228:229], v56 src0_sel:WORD_1
	v_cvt_pk_f32_fp8_e32 v[230:231], v57
	v_cvt_pk_f32_fp8_sdwa v[232:233], v57 src0_sel:WORD_1
	v_pk_fma_f32 v[132:133], v[130:131], v[132:133], v[134:135] op_sel_hi:[0,1,1]
	v_pk_fma_f32 v[134:135], v[130:131], v[228:229], v[216:217] op_sel_hi:[0,1,1]
	v_pk_fma_f32 v[216:217], v[130:131], v[230:231], v[218:219] op_sel_hi:[0,1,1]
	v_pk_fma_f32 v[218:219], v[130:131], v[232:233], v[220:221] op_sel_hi:[0,1,1]
	v_cvt_pk_f32_fp8_e32 v[220:221], v58
	v_cvt_pk_f32_fp8_sdwa v[228:229], v58 src0_sel:WORD_1
	v_cvt_pk_f32_fp8_e32 v[230:231], v59
	v_cvt_pk_f32_fp8_sdwa v[232:233], v59 src0_sel:WORD_1
	v_pk_fma_f32 v[220:221], v[130:131], v[220:221], v[222:223] op_sel_hi:[0,1,1]
	v_pk_fma_f32 v[222:223], v[130:131], v[228:229], v[224:225] op_sel_hi:[0,1,1]
	s_waitcnt vmcnt(17)
	s_and_b32 s101, s1, 3
	v_lshl_add_u32 v253, s101, 8, v252
	ds_read_b32 v210, v253
	ds_read_b32 v211, v253 offset:1024
	v_cvt_pk_f32_fp8_sdwa v[228:229], v60 src0_sel:WORD_1
	v_pk_fma_f32 v[224:225], v[130:131], v[230:231], v[226:227] op_sel_hi:[0,1,1]
	v_cvt_pk_f32_fp8_e32 v[226:227], v60
	v_cvt_pk_f32_fp8_e32 v[230:231], v61
	v_pk_fma_f32 v[128:129], v[130:131], v[232:233], v[128:129] op_sel_hi:[0,1,1]
	v_mov_b32_e32 v130, v131
	v_cvt_pk_f32_fp8_sdwa v[232:233], v61 src0_sel:WORD_1
	v_pk_fma_f32 v[134:135], v[130:131], v[228:229], v[134:135] op_sel_hi:[0,1,1]
	v_cvt_pk_f32_fp8_sdwa v[228:229], v62 src0_sel:WORD_1
	v_pk_fma_f32 v[132:133], v[130:131], v[226:227], v[132:133] op_sel_hi:[0,1,1]
	v_pk_fma_f32 v[216:217], v[130:131], v[230:231], v[216:217] op_sel_hi:[0,1,1]
	v_cvt_pk_f32_fp8_e32 v[226:227], v62
	v_cvt_pk_f32_fp8_e32 v[230:231], v63
	v_pk_fma_f32 v[218:219], v[130:131], v[232:233], v[218:219] op_sel_hi:[0,1,1]
	v_cvt_pk_f32_fp8_sdwa v[232:233], v63 src0_sel:WORD_1
	v_pk_fma_f32 v[222:223], v[130:131], v[228:229], v[222:223] op_sel_hi:[0,1,1]
	v_pk_fma_f32 v[220:221], v[130:131], v[226:227], v[220:221] op_sel_hi:[0,1,1]
	v_pk_fma_f32 v[224:225], v[130:131], v[230:231], v[224:225] op_sel_hi:[0,1,1]
	v_pk_fma_f32 v[128:129], v[130:131], v[232:233], v[128:129] op_sel_hi:[0,1,1]
	v_permlane32_swap_b32 v134, v222
	v_permlane32_swap_b32 v135, v223
	v_permlane32_swap_b32 v132, v220
	v_permlane32_swap_b32 v133, v221
	v_permlane32_swap_b32 v216, v224
	v_permlane32_swap_b32 v217, v225
	v_permlane32_swap_b32 v218, v128
	v_permlane32_swap_b32 v219, v129
	v_pk_add_f32 v[130:131], v[132:133], v[220:221]
	v_pk_add_f32 v[132:133], v[134:135], v[222:223]
	v_pk_add_f32 v[134:135], v[216:217], v[224:225]
	v_pk_add_f32 v[128:129], v[218:219], v[128:129]
	s_nop 1
	v_permlane16_swap_b32 v130, v134
	v_permlane16_swap_b32 v131, v135
	v_permlane16_swap_b32 v132, v128
	v_permlane16_swap_b32 v133, v129
	v_pk_add_f32 v[130:131], v[130:131], v[134:135]
	v_pk_add_f32 v[132:133], v[132:133], v[128:129]
	s_cmp_lg_u32 s1, 0
	s_nop 1
	v_add_f32_dpp v128, v130, v130 row_ror:8 row_mask:0xf bank_mask:0x3
	v_add_f32_dpp v128, v132, v132 row_ror:8 row_mask:0xf bank_mask:0xc
	v_add_f32_dpp v129, v131, v131 row_ror:8 row_mask:0xf bank_mask:0x3
	v_add_f32_dpp v129, v133, v133 row_ror:8 row_mask:0xf bank_mask:0xc
	v_lshlrev_b32_e32 v138, 2, v214
	s_cbranch_scc1 .LBB0_936
	global_load_dwordx2 v[178:179], v138, s[46:47]
	global_load_dwordx2 v[180:181], v138, s[48:49]
.LBB0_936:
	s_waitcnt lgkmcnt(0)
	v_lshlrev_b32_e32 v132, 16, v210
	v_and_b32_e32 v133, 0xffff0000, v210
	v_lshlrev_b32_e32 v134, 16, v211
	v_and_b32_e32 v135, 0xffff0000, v211
	v_readlane_b32 s98, v248, s1
	v_readlane_b32 s99, v249, s1
	v_or_b32_e32 v214, s1, v176
	s_waitcnt lgkmcnt(0)
	ds_bpermute_b32 v128, v250, v128
	ds_bpermute_b32 v129, v250, v129
	v_pk_fma_f32 v[130:131], v[132:133], s[74:75], v[134:135] op_sel_hi:[1,0,1]
	v_pk_add_f32 v[130:131], v[130:131], s[98:99] op_sel_hi:[1,0] neg_lo:[0,1] neg_hi:[0,1]
	s_add_i32 s61, s0, 2
	v_pk_mul_f32 v[130:131], s[98:99], v[130:131] op_sel:[1,0]
	s_cmpk_gt_u32 s0, 0xfd
	s_waitcnt vmcnt(0)
	v_pk_fma_f32 v[130:131], v[130:131], v[178:179], v[180:181]
	s_cselect_b64 s[0:1], -1, 0
	v_lshl_or_b32 v214, v214, 13, v138
	s_waitcnt lgkmcnt(0)
	v_pk_fma_f32 v[128:129], v[130:131], s[74:75], v[128:129] op_sel_hi:[1,0,1]
	s_and_b64 vcc, exec, s[0:1]
	global_store_dwordx2 v214, v[128:129], s[78:79] nt
	s_cbranch_vccnz .LBB0_933
	s_and_b32 s15, s17, 0x700
	v_lshl_add_u32 v0, s15, 2, v189
	ds_read_b128 v[6:9], v0
	ds_read_b128 v[22:25], v0 offset:16
	ds_read_b128 v[38:41], v0 offset:32
	ds_read_b128 v[54:57], v0 offset:48
	s_and_b32 s14, s34, 0x3e00000
	s_add_u32 s14, s38, s14
	s_waitcnt lgkmcnt(2)
	s_waitcnt lgkmcnt(1)
	s_waitcnt lgkmcnt(0)
	s_addc_u32 s15, s39, 0
	v_lshl_or_b32 v4, v7, 7, v137
	v_lshl_or_b32 v0, v6, 7, v174
	v_lshl_or_b32 v12, v9, 7, v137
	v_lshl_or_b32 v8, v8, 7, v174
	v_lshl_or_b32 v20, v23, 7, v137
	v_lshl_or_b32 v16, v22, 7, v174
	v_lshl_or_b32 v28, v25, 7, v137
	v_lshl_or_b32 v24, v24, 7, v174
	v_lshl_or_b32 v36, v39, 7, v137
	v_lshl_or_b32 v32, v38, 7, v174
	v_lshl_or_b32 v44, v41, 7, v137
	v_lshl_or_b32 v40, v40, 7, v174
	v_lshl_or_b32 v52, v55, 7, v137
	v_lshl_or_b32 v48, v54, 7, v174
	v_lshl_or_b32 v60, v57, 7, v137
	v_lshl_or_b32 v56, v56, 7, v174
	global_load_dwordx4 v[0:3], v0, s[14:15]
	s_nop 0
	global_load_dwordx4 v[4:7], v4, s[14:15]
	s_nop 0
	global_load_dwordx4 v[8:11], v8, s[14:15]
	s_nop 0
	global_load_dwordx4 v[12:15], v12, s[14:15]
	s_nop 0
	global_load_dwordx4 v[16:19], v16, s[14:15]
	s_nop 0
	global_load_dwordx4 v[20:23], v20, s[14:15]
	s_nop 0
	global_load_dwordx4 v[24:27], v24, s[14:15]
	s_nop 0
	global_load_dwordx4 v[28:31], v28, s[14:15]
	s_nop 0
	global_load_dwordx4 v[32:35], v32, s[14:15]
	s_nop 0
	global_load_dwordx4 v[36:39], v36, s[14:15]
	s_nop 0
	global_load_dwordx4 v[40:43], v40, s[14:15]
	s_nop 0
	global_load_dwordx4 v[44:47], v44, s[14:15]
	s_nop 0
	global_load_dwordx4 v[48:51], v48, s[14:15]
	s_nop 0
	global_load_dwordx4 v[52:55], v52, s[14:15]
	s_nop 0
	global_load_dwordx4 v[56:59], v56, s[14:15]
	s_nop 0
	global_load_dwordx4 v[60:63], v60, s[14:15]
	s_branch .LBB0_933
